# GEMM K-loop: pointer/counter SALU block moved in front of the loop-back barrier (loop-edge edit)
# speedup vs baseline: 1.0009x; 1.0009x over previous
.LBB0_332:
	s_add_i32 s69, s64, 2
	s_add_u32 s85, s8, 0x80
	s_addc_u32 s65, s9, 0
	s_add_i32 s80, 0, 0x10000
	s_cmp_eq_u32 s19, s64
	s_cselect_b32 s65, s15, s65
	s_cselect_b32 s64, s14, s85
	s_cselect_b32 vcc_hi, s83, s68
	s_cselect_b32 vcc_lo, s82, s16
	s_add_i32 s81, 0, 0x14000
	v_add_u32_e32 v140, s80, v206
	v_add_u32_e32 v156, s81, v206
	ds_read_b128 v[128:131], v140
	ds_read_b128 v[132:135], v140 offset:1024
	ds_read_b128 v[136:139], v140 offset:2048
	ds_read_b128 v[140:143], v140 offset:3072
	ds_read_b128 v[144:147], v156
	ds_read_b128 v[148:151], v156 offset:1024
	ds_read_b128 v[152:155], v156 offset:2048
	ds_read_b128 v[156:159], v156 offset:3072
	v_lshl_add_u64 v[198:199], s[8:9], 0, v[186:187]
	s_add_i32 m0, s73, 0xc000
	ds_read_b128 v[160:163], v211
	ds_read_b128 v[164:167], v211 offset:1024
	ds_read_b128 v[190:193], v211 offset:2048
	ds_read_b128 v[194:197], v211 offset:3072
	ds_read_b128 v[212:215], v211 offset:4096
	ds_read_b128 v[216:219], v211 offset:5120
	ds_read_b128 v[220:223], v211 offset:6144
	ds_read_b128 v[224:227], v211 offset:7168
	global_load_lds_dwordx4 v[198:199], off
	v_lshl_add_u64 v[198:199], s[8:9], 0, v[188:189]
	s_add_i32 m0, s73, 0xe000
	s_nop 0
	global_load_lds_dwordx4 v[198:199], off
	s_waitcnt vmcnt(8)
	s_waitcnt lgkmcnt(0)
	s_barrier
	s_setprio 1
	s_waitcnt lgkmcnt(0)
	v_mfma_f32_16x16x32_bf16 v[124:127], v[128:131], v[160:163], v[124:127]
	v_mfma_f32_16x16x32_bf16 v[120:123], v[136:139], v[160:163], v[120:123]
	v_mfma_f32_16x16x32_bf16 v[108:111], v[128:131], v[190:193], v[108:111]
	v_mfma_f32_16x16x32_bf16 v[104:107], v[136:139], v[190:193], v[104:107]
	v_mfma_f32_16x16x32_bf16 v[92:95], v[128:131], v[212:215], v[92:95]
	v_mfma_f32_16x16x32_bf16 v[88:91], v[136:139], v[212:215], v[88:91]
	v_mfma_f32_16x16x32_bf16 v[76:79], v[128:131], v[220:223], v[76:79]
	v_mfma_f32_16x16x32_bf16 v[72:75], v[136:139], v[220:223], v[72:75]
	v_mfma_f32_16x16x32_bf16 v[124:127], v[132:135], v[164:167], v[124:127]
	v_mfma_f32_16x16x32_bf16 v[120:123], v[140:143], v[164:167], v[120:123]
	v_mfma_f32_16x16x32_bf16 v[108:111], v[132:135], v[194:197], v[108:111]
	v_mfma_f32_16x16x32_bf16 v[104:107], v[140:143], v[194:197], v[104:107]
	v_mfma_f32_16x16x32_bf16 v[92:95], v[132:135], v[216:219], v[92:95]
	v_mfma_f32_16x16x32_bf16 v[88:91], v[140:143], v[216:219], v[88:91]
	v_mfma_f32_16x16x32_bf16 v[76:79], v[132:135], v[224:227], v[76:79]
	v_mfma_f32_16x16x32_bf16 v[72:75], v[140:143], v[224:227], v[72:75]
	s_setprio 0
	s_setprio 1
	v_mfma_f32_16x16x32_bf16 v[116:119], v[144:147], v[160:163], v[116:119]
	v_mfma_f32_16x16x32_bf16 v[112:115], v[152:155], v[160:163], v[112:115]
	v_mfma_f32_16x16x32_bf16 v[100:103], v[144:147], v[190:193], v[100:103]
	v_mfma_f32_16x16x32_bf16 v[96:99], v[152:155], v[190:193], v[96:99]
	v_mfma_f32_16x16x32_bf16 v[84:87], v[144:147], v[212:215], v[84:87]
	v_mfma_f32_16x16x32_bf16 v[80:83], v[152:155], v[212:215], v[80:83]
	v_mfma_f32_16x16x32_bf16 v[68:71], v[144:147], v[220:223], v[68:71]
	v_mfma_f32_16x16x32_bf16 v[64:67], v[152:155], v[220:223], v[64:67]
	v_mfma_f32_16x16x32_bf16 v[116:119], v[148:151], v[164:167], v[116:119]
	v_mfma_f32_16x16x32_bf16 v[112:115], v[156:159], v[164:167], v[112:115]
	v_mfma_f32_16x16x32_bf16 v[100:103], v[148:151], v[194:197], v[100:103]
	v_mfma_f32_16x16x32_bf16 v[96:99], v[156:159], v[194:197], v[96:99]
	v_mfma_f32_16x16x32_bf16 v[84:87], v[148:151], v[216:219], v[84:87]
	v_mfma_f32_16x16x32_bf16 v[80:83], v[156:159], v[216:219], v[80:83]
	v_mfma_f32_16x16x32_bf16 v[68:71], v[148:151], v[224:227], v[68:71]
	v_mfma_f32_16x16x32_bf16 v[64:67], v[156:159], v[224:227], v[64:67]
	s_setprio 0
	s_barrier
	s_add_i32 s80, s80, s72
	v_lshl_add_u64 v[198:199], vcc, 0, v[176:177]
	s_mov_b32 m0, s80
	ds_read_b128 v[160:163], v211 offset:16384
	ds_read_b128 v[164:167], v211 offset:17408
	ds_read_b128 v[190:193], v211 offset:18432
	ds_read_b128 v[194:197], v211 offset:19456
	ds_read_b128 v[212:215], v211 offset:20480
	ds_read_b128 v[216:219], v211 offset:21504
	ds_read_b128 v[220:223], v211 offset:22528
	ds_read_b128 v[224:227], v211 offset:23552
	global_load_lds_dwordx4 v[198:199], off
	s_add_i32 m0, s80, 0x2000
	v_lshl_add_u64 v[228:229], vcc, 0, v[180:181]
	s_add_u32 vcc_lo, vcc_lo, s74
	s_addc_u32 vcc_hi, vcc_hi, 0
	s_add_i32 s80, s81, s72
	global_load_lds_dwordx4 v[228:229], off
	v_lshl_add_u64 v[230:231], vcc, 0, v[176:177]
	s_mov_b32 m0, s80
	v_lshl_add_u64 v[232:233], vcc, 0, v[180:181]
	global_load_lds_dwordx4 v[230:231], off
	s_add_i32 m0, s80, 0x2000
	v_lshl_add_u64 v[234:235], s[64:65], 0, v[174:175]
	global_load_lds_dwordx4 v[232:233], off
	s_mov_b32 m0, s73
	v_lshl_add_u64 v[236:237], s[64:65], 0, v[178:179]
	global_load_lds_dwordx4 v[234:235], off
	s_mov_b32 m0, s92
	s_nop 0
	global_load_lds_dwordx4 v[236:237], off
	s_waitcnt vmcnt(8)
	s_waitcnt lgkmcnt(0)
	s_barrier
	s_setprio 1
	s_waitcnt lgkmcnt(0)
	v_mfma_f32_16x16x32_bf16 v[60:63], v[128:131], v[160:163], v[60:63]
	v_mfma_f32_16x16x32_bf16 v[56:59], v[136:139], v[160:163], v[56:59]
	v_mfma_f32_16x16x32_bf16 v[44:47], v[128:131], v[190:193], v[44:47]
	v_mfma_f32_16x16x32_bf16 v[40:43], v[136:139], v[190:193], v[40:43]
	v_mfma_f32_16x16x32_bf16 v[28:31], v[128:131], v[212:215], v[28:31]
	v_mfma_f32_16x16x32_bf16 v[24:27], v[136:139], v[212:215], v[24:27]
	v_mfma_f32_16x16x32_bf16 v[12:15], v[128:131], v[220:223], v[12:15]
	v_mfma_f32_16x16x32_bf16 v[8:11], v[136:139], v[220:223], v[8:11]
	v_mfma_f32_16x16x32_bf16 v[60:63], v[132:135], v[164:167], v[60:63]
	v_mfma_f32_16x16x32_bf16 v[56:59], v[140:143], v[164:167], v[56:59]
	v_mfma_f32_16x16x32_bf16 v[44:47], v[132:135], v[194:197], v[44:47]
	v_mfma_f32_16x16x32_bf16 v[40:43], v[140:143], v[194:197], v[40:43]
	v_mfma_f32_16x16x32_bf16 v[28:31], v[132:135], v[216:219], v[28:31]
	v_mfma_f32_16x16x32_bf16 v[24:27], v[140:143], v[216:219], v[24:27]
	v_mfma_f32_16x16x32_bf16 v[12:15], v[132:135], v[224:227], v[12:15]
	v_mfma_f32_16x16x32_bf16 v[8:11], v[140:143], v[224:227], v[8:11]
	s_setprio 0
	s_setprio 1
	v_mfma_f32_16x16x32_bf16 v[52:55], v[144:147], v[160:163], v[52:55]
	v_mfma_f32_16x16x32_bf16 v[48:51], v[152:155], v[160:163], v[48:51]
	v_mfma_f32_16x16x32_bf16 v[36:39], v[144:147], v[190:193], v[36:39]
	v_mfma_f32_16x16x32_bf16 v[32:35], v[152:155], v[190:193], v[32:35]
	v_mfma_f32_16x16x32_bf16 v[20:23], v[144:147], v[212:215], v[20:23]
	v_mfma_f32_16x16x32_bf16 v[16:19], v[152:155], v[212:215], v[16:19]
	v_mfma_f32_16x16x32_bf16 v[4:7], v[144:147], v[220:223], v[4:7]
	v_mfma_f32_16x16x32_bf16 v[0:3], v[152:155], v[220:223], v[0:3]
	v_mfma_f32_16x16x32_bf16 v[52:55], v[148:151], v[164:167], v[52:55]
	v_mfma_f32_16x16x32_bf16 v[48:51], v[156:159], v[164:167], v[48:51]
	v_mfma_f32_16x16x32_bf16 v[36:39], v[148:151], v[194:197], v[36:39]
	v_mfma_f32_16x16x32_bf16 v[32:35], v[156:159], v[194:197], v[32:35]
	v_mfma_f32_16x16x32_bf16 v[20:23], v[148:151], v[216:219], v[20:23]
	v_mfma_f32_16x16x32_bf16 v[16:19], v[156:159], v[216:219], v[16:19]
	v_mfma_f32_16x16x32_bf16 v[4:7], v[148:151], v[224:227], v[4:7]
	v_mfma_f32_16x16x32_bf16 v[0:3], v[156:159], v[224:227], v[0:3]
	s_setprio 0
	s_barrier
	s_add_i32 s80, 0, 0x18000
	s_add_i32 s81, 0, 0x1c000
	v_add_u32_e32 v140, s80, v206
	v_add_u32_e32 v156, s81, v206
	ds_read_b128 v[128:131], v140
	ds_read_b128 v[132:135], v140 offset:1024
	ds_read_b128 v[136:139], v140 offset:2048
	ds_read_b128 v[140:143], v140 offset:3072
	ds_read_b128 v[144:147], v156
	ds_read_b128 v[148:151], v156 offset:1024
	ds_read_b128 v[152:155], v156 offset:2048
	ds_read_b128 v[156:159], v156 offset:3072
	s_add_u32 s64, s64, s74
	s_addc_u32 s65, s65, 0
	s_mov_b32 m0, s93
	v_lshl_add_u64 v[238:239], s[64:65], 0, v[174:175]
	ds_read_b128 v[160:163], v211 offset:32768
	ds_read_b128 v[164:167], v211 offset:33792
	ds_read_b128 v[190:193], v211 offset:34816
	ds_read_b128 v[194:197], v211 offset:35840
	ds_read_b128 v[212:215], v211 offset:36864
	ds_read_b128 v[216:219], v211 offset:37888
	ds_read_b128 v[220:223], v211 offset:38912
	ds_read_b128 v[224:227], v211 offset:39936
	global_load_lds_dwordx4 v[238:239], off
	v_lshl_add_u64 v[238:239], s[64:65], 0, v[178:179]
	s_mov_b32 m0, s94
	s_nop 0
	global_load_lds_dwordx4 v[238:239], off
	s_waitcnt vmcnt(8)
	s_waitcnt lgkmcnt(0)
	s_barrier
	s_setprio 1
	s_waitcnt lgkmcnt(0)
	v_mfma_f32_16x16x32_bf16 v[124:127], v[128:131], v[160:163], v[124:127]
	v_mfma_f32_16x16x32_bf16 v[120:123], v[136:139], v[160:163], v[120:123]
	v_mfma_f32_16x16x32_bf16 v[108:111], v[128:131], v[190:193], v[108:111]
	v_mfma_f32_16x16x32_bf16 v[104:107], v[136:139], v[190:193], v[104:107]
	v_mfma_f32_16x16x32_bf16 v[92:95], v[128:131], v[212:215], v[92:95]
	v_mfma_f32_16x16x32_bf16 v[88:91], v[136:139], v[212:215], v[88:91]
	v_mfma_f32_16x16x32_bf16 v[76:79], v[128:131], v[220:223], v[76:79]
	v_mfma_f32_16x16x32_bf16 v[72:75], v[136:139], v[220:223], v[72:75]
	v_mfma_f32_16x16x32_bf16 v[124:127], v[132:135], v[164:167], v[124:127]
	v_mfma_f32_16x16x32_bf16 v[120:123], v[140:143], v[164:167], v[120:123]
	v_mfma_f32_16x16x32_bf16 v[108:111], v[132:135], v[194:197], v[108:111]
	v_mfma_f32_16x16x32_bf16 v[104:107], v[140:143], v[194:197], v[104:107]
	v_mfma_f32_16x16x32_bf16 v[92:95], v[132:135], v[216:219], v[92:95]
	v_mfma_f32_16x16x32_bf16 v[88:91], v[140:143], v[216:219], v[88:91]
	v_mfma_f32_16x16x32_bf16 v[76:79], v[132:135], v[224:227], v[76:79]
	v_mfma_f32_16x16x32_bf16 v[72:75], v[140:143], v[224:227], v[72:75]
	s_setprio 0
	s_setprio 1
	v_mfma_f32_16x16x32_bf16 v[116:119], v[144:147], v[160:163], v[116:119]
	v_mfma_f32_16x16x32_bf16 v[112:115], v[152:155], v[160:163], v[112:115]
	v_mfma_f32_16x16x32_bf16 v[100:103], v[144:147], v[190:193], v[100:103]
	v_mfma_f32_16x16x32_bf16 v[96:99], v[152:155], v[190:193], v[96:99]
	v_mfma_f32_16x16x32_bf16 v[84:87], v[144:147], v[212:215], v[84:87]
	v_mfma_f32_16x16x32_bf16 v[80:83], v[152:155], v[212:215], v[80:83]
	v_mfma_f32_16x16x32_bf16 v[68:71], v[144:147], v[220:223], v[68:71]
	v_mfma_f32_16x16x32_bf16 v[64:67], v[152:155], v[220:223], v[64:67]
	v_mfma_f32_16x16x32_bf16 v[116:119], v[148:151], v[164:167], v[116:119]
	v_mfma_f32_16x16x32_bf16 v[112:115], v[156:159], v[164:167], v[112:115]
	v_mfma_f32_16x16x32_bf16 v[100:103], v[148:151], v[194:197], v[100:103]
	v_mfma_f32_16x16x32_bf16 v[96:99], v[156:159], v[194:197], v[96:99]
	v_mfma_f32_16x16x32_bf16 v[84:87], v[148:151], v[216:219], v[84:87]
	v_mfma_f32_16x16x32_bf16 v[80:83], v[156:159], v[216:219], v[80:83]
	v_mfma_f32_16x16x32_bf16 v[68:71], v[148:151], v[224:227], v[68:71]
	v_mfma_f32_16x16x32_bf16 v[64:67], v[156:159], v[224:227], v[64:67]
	s_setprio 0
	s_barrier
	s_add_i32 s64, s80, s72
	v_lshl_add_u64 v[198:199], v[198:199], 0, s[88:89]
	s_mov_b32 m0, s64
	ds_read_b128 v[160:163], v211 offset:49152
	ds_read_b128 v[164:167], v211 offset:50176
	ds_read_b128 v[190:193], v211 offset:51200
	ds_read_b128 v[194:197], v211 offset:52224
	ds_read_b128 v[212:215], v211 offset:53248
	ds_read_b128 v[216:219], v211 offset:54272
	ds_read_b128 v[220:223], v211 offset:55296
	ds_read_b128 v[224:227], v211 offset:56320
	global_load_lds_dwordx4 v[198:199], off
	v_lshl_add_u64 v[198:199], v[228:229], 0, s[88:89]
	s_add_i32 m0, s64, 0x2000
	s_add_i32 s64, s81, s72
	global_load_lds_dwordx4 v[198:199], off
	v_lshl_add_u64 v[198:199], v[230:231], 0, s[88:89]
	s_mov_b32 m0, s64
	s_nop 0
	global_load_lds_dwordx4 v[198:199], off
	v_lshl_add_u64 v[198:199], v[232:233], 0, s[88:89]
	s_add_i32 m0, s64, 0x2000
	s_nop 0
	global_load_lds_dwordx4 v[198:199], off
	v_lshl_add_u64 v[198:199], v[234:235], 0, s[88:89]
	s_mov_b32 m0, s95
	s_nop 0
	global_load_lds_dwordx4 v[198:199], off
	v_lshl_add_u64 v[198:199], v[236:237], 0, s[88:89]
	s_mov_b32 m0, s98
	s_nop 0
	global_load_lds_dwordx4 v[198:199], off
	s_waitcnt vmcnt(8)
	s_waitcnt lgkmcnt(0)
	s_barrier
	s_setprio 1
	s_waitcnt lgkmcnt(0)
	v_mfma_f32_16x16x32_bf16 v[60:63], v[128:131], v[160:163], v[60:63]
	v_mfma_f32_16x16x32_bf16 v[56:59], v[136:139], v[160:163], v[56:59]
	v_mfma_f32_16x16x32_bf16 v[44:47], v[128:131], v[190:193], v[44:47]
	v_mfma_f32_16x16x32_bf16 v[40:43], v[136:139], v[190:193], v[40:43]
	v_mfma_f32_16x16x32_bf16 v[28:31], v[128:131], v[212:215], v[28:31]
	v_mfma_f32_16x16x32_bf16 v[24:27], v[136:139], v[212:215], v[24:27]
	v_mfma_f32_16x16x32_bf16 v[12:15], v[128:131], v[220:223], v[12:15]
	v_mfma_f32_16x16x32_bf16 v[8:11], v[136:139], v[220:223], v[8:11]
	v_mfma_f32_16x16x32_bf16 v[60:63], v[132:135], v[164:167], v[60:63]
	v_mfma_f32_16x16x32_bf16 v[56:59], v[140:143], v[164:167], v[56:59]
	v_mfma_f32_16x16x32_bf16 v[44:47], v[132:135], v[194:197], v[44:47]
	v_mfma_f32_16x16x32_bf16 v[40:43], v[140:143], v[194:197], v[40:43]
	v_mfma_f32_16x16x32_bf16 v[28:31], v[132:135], v[216:219], v[28:31]
	v_mfma_f32_16x16x32_bf16 v[24:27], v[140:143], v[216:219], v[24:27]
	v_mfma_f32_16x16x32_bf16 v[12:15], v[132:135], v[224:227], v[12:15]
	v_mfma_f32_16x16x32_bf16 v[8:11], v[140:143], v[224:227], v[8:11]
	s_setprio 0
	s_setprio 1
	v_mfma_f32_16x16x32_bf16 v[52:55], v[144:147], v[160:163], v[52:55]
	v_mfma_f32_16x16x32_bf16 v[48:51], v[152:155], v[160:163], v[48:51]
	v_mfma_f32_16x16x32_bf16 v[36:39], v[144:147], v[190:193], v[36:39]
	v_mfma_f32_16x16x32_bf16 v[32:35], v[152:155], v[190:193], v[32:35]
	v_mfma_f32_16x16x32_bf16 v[20:23], v[144:147], v[212:215], v[20:23]
	v_mfma_f32_16x16x32_bf16 v[16:19], v[152:155], v[212:215], v[16:19]
	v_mfma_f32_16x16x32_bf16 v[4:7], v[144:147], v[220:223], v[4:7]
	v_mfma_f32_16x16x32_bf16 v[0:3], v[152:155], v[220:223], v[0:3]
	v_mfma_f32_16x16x32_bf16 v[52:55], v[148:151], v[164:167], v[52:55]
	v_mfma_f32_16x16x32_bf16 v[48:51], v[156:159], v[164:167], v[48:51]
	v_mfma_f32_16x16x32_bf16 v[36:39], v[148:151], v[194:197], v[36:39]
	v_mfma_f32_16x16x32_bf16 v[32:35], v[156:159], v[194:197], v[32:35]
	v_mfma_f32_16x16x32_bf16 v[20:23], v[148:151], v[216:219], v[20:23]
	v_mfma_f32_16x16x32_bf16 v[16:19], v[156:159], v[216:219], v[16:19]
	v_mfma_f32_16x16x32_bf16 v[4:7], v[148:151], v[224:227], v[4:7]
	v_mfma_f32_16x16x32_bf16 v[0:3], v[156:159], v[224:227], v[0:3]
	s_setprio 0
	s_add_u32 s8, s8, 0x100
	s_addc_u32 s9, s9, 0
	s_add_u32 s16, s16, 0x100
	s_addc_u32 s68, s68, 0
	s_cmp_ge_u32 s69, s96
	s_mov_b32 s64, s69
	s_barrier
	s_cbranch_scc0 .LBB0_332
	s_and_b64 vcc, exec, s[12:13]
	s_cbranch_vccnz .LBB0_336
	s_cmp_lt_i32 s35, 2
	s_mov_b64 s[8:9], -1
	s_cbranch_scc0 .LBB0_337
